# v65 + attention running max updated / O rescaled only when a row max grows by more than 8 log2 units (lazy rescale, exact reformulation; same dtypes)
# speedup vs baseline: 1.0169x; 1.0169x over previous
; #define LAS __attribute__((address_space(3)))
; DI float shfl_xor_l(float v, int lane, int m) { return __int_as_float(__builtin_amdgcn_ds_bpermute((lane ^ m) << 2, __float_as_int(v))); }
; #define A_LOAD(kt) do { const size_t ko = (size_t)(kt) * 64; st0 = *(const u32x4*)(kn_src + ko * 2048); st1 = *(const u32x4*)(kn_src + (ko + 32) * 2048); \
;         st2 = *(const u32x4*)(kr_src + ko * 64); st3 = *(const u32x4*)(v_src + ko); st4 = *(const u32x4*)(v_src + ko + (size_t)64 * 8192); } while (0)
; DI void attn_unit(LAS unsigned char* lds, int wid, int b, int h, int qb) {
;     ...
;     A_LOAD(0); A_WRITE(0); __syncthreads();
;     for (int kt = 0; kt < nkt; ++kt) {
;         const int buf = kt & 1;
;         if (kt + 1 < nkt) A_LOAD(kt + 1);
;         if (kt <= cq) {
;             LAS unsigned char* kb = lds + buf * ABUF; LAS unsigned char* vb = kb + KBYTES;
;             f32x16 s0, s1;
; #pragma unroll
;             for (int i = 0; i < 16; ++i) { s0[i] = 0.f; s1[i] = 0.f; }
;     ...
;             bf16x8 ka[3][2];
;             ka[0][0] = KLD(0, 0); ka[0][1] = KLD(0, 1); ka[1][0] = KLD(1, 0); ka[1][1] = KLD(1, 1);
; #pragma unroll
;             for (int ks = 0; ks < 12; ++ks) {
;                 if (ks + 2 < 12) { ka[(ks + 2) % 3][0] = KLD(ks + 2, 0); ka[(ks + 2) % 3][1] = KLD(ks + 2, 1); }
;                 s0 = __builtin_amdgcn_mfma_f32_32x32x16_bf16(ka[ks % 3][0], qf[ks], s0, 0, 0, 0); s1 = __builtin_amdgcn_mfma_f32_32x32x16_bf16(ka[ks % 3][1], qf[ks], s1, 0, 0, 0);
;                 __builtin_amdgcn_sched_barrier(0); }
;             u32x4 vf[2][4];
; #pragma unroll
;             for (int dt = 0; dt < 4; ++dt) VLD(vf[0][dt], 0, dt);
;             float mx = s0[0];
; #pragma unroll
;             for (int i = 1; i < 16; ++i) mx = fmaxf(mx, s0[i]);
; #pragma unroll
;             for (int i = 0; i < 16; ++i) mx = fmaxf(mx, s1[i]);
;             mx = fmaxf(mx, shfl_xor_l(mx, lane, 32));
;             const float mnew = fmaxf(mrow, mx), alpha = __builtin_amdgcn_exp2f(mrow - mnew); mrow = mnew;
;             float ls = 0.f;
; #pragma unroll
;             for (int i = 0; i < 16; ++i) { s0[i] = __builtin_amdgcn_exp2f(s0[i] - mnew); s1[i] = __builtin_amdgcn_exp2f(s1[i] - mnew); ls += s0[i] + s1[i]; }
;             lrow = lrow * alpha + ls;
;             if (__builtin_amdgcn_ballot_w64(alpha != 1.f) != 0ull) {
.LBB0_1079:
	v_lshl_add_u64 v[66:67], s[24:25], 0, v[194:195]
	v_add_co_u32_e32 v68, vcc, 0x11140000, v66
	s_and_b32 s65, s64, 1
	s_nop 0
	v_addc_co_u32_e32 v69, vcc, 0, v67, vcc
	v_add_co_u32_e32 v66, vcc, 0x11160000, v66
	s_cmp_gt_u32 s64, s62
	s_nop 0
	v_addc_co_u32_e32 v67, vcc, 0, v67, vcc
	global_load_dwordx4 v[146:149], v[68:69], off
	global_load_dwordx4 v[150:153], v[66:67], off
	v_lshl_add_u64 v[68:69], s[24:25], 0, v[190:191]
	v_add_co_u32_e32 v70, vcc, 0x13100000, v68
	v_lshl_add_u64 v[66:67], s[24:25], 0, v[192:193]
	s_nop 0
	v_addc_co_u32_e32 v71, vcc, 0, v69, vcc
	global_load_dwordx4 v[154:157], v[66:67], off
	global_load_dwordx4 v[158:161], v[70:71], off offset:128
	v_add_co_u32_e32 v66, vcc, 0x13200000, v68
	s_nop 1
	v_addc_co_u32_e32 v67, vcc, 0, v69, vcc
	global_load_dwordx4 v[162:165], v[66:67], off offset:128
	s_cbranch_scc1 .LBB0_1083
	s_mul_i32 s66, s65, 0xa800
	s_add_i32 s66, s66, 0
	v_add3_u32 v171, s66, v199, v202
	ds_read_b128 v[66:69], v171
	ds_read_b128 v[166:169], v171 offset:32
	ds_read_b128 v[82:85], v171 offset:12800
	ds_read_b128 v[172:175], v171 offset:64
	ds_read_b128 v[176:179], v171 offset:12832
	ds_read_b128 v[204:207], v171 offset:12864
	s_waitcnt lgkmcnt(3)
	v_mfma_f32_32x32x16_bf16 v[82:97], v[82:85], v[142:145], 0
	v_mfma_f32_32x32x16_bf16 v[66:81], v[66:69], v[142:145], 0
	v_mfma_f32_32x32x16_bf16 v[66:81], v[166:169], v[138:141], v[66:81]
	ds_read_b128 v[166:169], v171 offset:96
	ds_read_b128 v[208:211], v171 offset:12896
	s_waitcnt lgkmcnt(3)
	v_mfma_f32_32x32x16_bf16 v[82:97], v[176:179], v[138:141], v[82:97]
	v_mfma_f32_32x32x16_bf16 v[66:81], v[172:175], v[134:137], v[66:81]
	ds_read_b128 v[172:175], v171 offset:128
	ds_read_b128 v[176:179], v171 offset:12928
	s_waitcnt lgkmcnt(4)
	v_mfma_f32_32x32x16_bf16 v[82:97], v[204:207], v[134:137], v[82:97]
	s_waitcnt lgkmcnt(3)
	v_mfma_f32_32x32x16_bf16 v[66:81], v[166:169], v[130:133], v[66:81]
	ds_read_b128 v[166:169], v171 offset:160
	ds_read_b128 v[204:207], v171 offset:12960
	s_waitcnt lgkmcnt(4)
	v_mfma_f32_32x32x16_bf16 v[82:97], v[208:211], v[130:133], v[82:97]
	s_waitcnt lgkmcnt(3)
	v_mfma_f32_32x32x16_bf16 v[66:81], v[172:175], v[126:129], v[66:81]
	ds_read_b128 v[172:175], v171 offset:192
	ds_read_b128 v[208:211], v171 offset:12992
	s_waitcnt lgkmcnt(4)
	v_mfma_f32_32x32x16_bf16 v[82:97], v[176:179], v[126:129], v[82:97]
	s_waitcnt lgkmcnt(3)
	v_mfma_f32_32x32x16_bf16 v[66:81], v[166:169], v[122:125], v[66:81]
	ds_read_b128 v[166:169], v171 offset:224
	ds_read_b128 v[176:179], v171 offset:13024
	s_waitcnt lgkmcnt(4)
	v_mfma_f32_32x32x16_bf16 v[82:97], v[204:207], v[122:125], v[82:97]
	s_waitcnt lgkmcnt(3)
	v_mfma_f32_32x32x16_bf16 v[66:81], v[172:175], v[118:121], v[66:81]
	ds_read_b128 v[172:175], v171 offset:256
	ds_read_b128 v[204:207], v171 offset:13056
	s_waitcnt lgkmcnt(4)
	v_mfma_f32_32x32x16_bf16 v[82:97], v[208:211], v[118:121], v[82:97]
	s_waitcnt lgkmcnt(3)
	v_mfma_f32_32x32x16_bf16 v[66:81], v[166:169], v[114:117], v[66:81]
	ds_read_b128 v[166:169], v171 offset:288
	ds_read_b128 v[208:211], v171 offset:13088
	s_waitcnt lgkmcnt(4)
	v_mfma_f32_32x32x16_bf16 v[82:97], v[176:179], v[114:117], v[82:97]
	s_waitcnt lgkmcnt(3)
	v_mfma_f32_32x32x16_bf16 v[66:81], v[172:175], v[110:113], v[66:81]
	ds_read_b128 v[172:175], v171 offset:320
	ds_read_b128 v[176:179], v171 offset:13120
	s_waitcnt lgkmcnt(4)
	v_mfma_f32_32x32x16_bf16 v[82:97], v[204:207], v[110:113], v[82:97]
	s_waitcnt lgkmcnt(3)
	v_mfma_f32_32x32x16_bf16 v[66:81], v[166:169], v[106:109], v[66:81]
	ds_read_b128 v[166:169], v171 offset:352
	ds_read_b128 v[212:215], v171 offset:13152
	s_waitcnt lgkmcnt(4)
	v_mfma_f32_32x32x16_bf16 v[82:97], v[208:211], v[106:109], v[82:97]
	s_waitcnt lgkmcnt(3)
	v_mfma_f32_32x32x16_bf16 v[66:81], v[172:175], v[102:105], v[66:81]
	s_waitcnt lgkmcnt(2)
	v_mfma_f32_32x32x16_bf16 v[82:97], v[176:179], v[102:105], v[82:97]
	s_waitcnt lgkmcnt(1)
	v_mfma_f32_32x32x16_bf16 v[66:81], v[166:169], v[98:101], v[66:81]
	v_add_u32_e32 v171, s66, v184
	v_add_u32_e32 v171, v171, v189
	v_add_u32_e32 v204, 0x6000, v171
	v_add_u32_e32 v205, 0x7000, v171
	v_add_u32_e32 v206, 0x8000, v171
	v_add_u32_e32 v207, 0x9000, v171
	ds_read2_b64 v[166:169], v204 offset0:128 offset1:130
	s_nop 4
	v_max_f32_e32 v172, v67, v67
	v_max_f32_e32 v173, v66, v66
	v_max_f32_e32 v172, v173, v172
	s_waitcnt lgkmcnt(1)
	v_mfma_f32_32x32x16_bf16 v[82:97], v[212:215], v[98:101], v[82:97]
	v_max3_f32 v172, v172, v68, v69
	v_max3_f32 v172, v172, v70, v71
	v_max3_f32 v172, v172, v72, v73
	v_max3_f32 v172, v172, v74, v75
	v_max3_f32 v172, v172, v76, v77
	v_max3_f32 v172, v172, v78, v79
	v_max3_f32 v172, v172, v80, v81
	s_nop 4
	v_max3_f32 v172, v172, v82, v83
	v_max3_f32 v172, v172, v84, v85
	v_max3_f32 v172, v172, v86, v87
	v_max3_f32 v172, v172, v88, v89
	v_max3_f32 v172, v172, v90, v91
	v_max3_f32 v172, v172, v92, v93
	v_max3_f32 v172, v172, v94, v95
	v_max3_f32 v172, v172, v96, v97
	ds_bpermute_b32 v173, v185, v172
	ds_read2_b64 v[178:181], v205 offset0:160 offset1:162
	ds_read2_b64 v[174:177], v206 offset0:192 offset1:194
	s_waitcnt lgkmcnt(2)
	v_max3_f32 v203, v170, v172, v173
	v_mov_b32_e32 v236, v170
	v_sub_f32_e32 v170, v170, v203
	v_cmp_gt_f32_e32 vcc, 0xc1000000, v170
	v_exp_f32_e32 v196, v170
	ds_read2_b64 v[170:173], v207 offset0:224 offset1:226
	s_cbranch_vccz .Lthr_0_keep
; DI void attn_unit(LAS unsigned char* lds, int wid, int b, int h, int qb) {
;     ...
;             if (__builtin_amdgcn_ballot_w64(alpha != 1.f) != 0ull) {
; #pragma unroll
;                 for (int dt = 0; dt < 4; ++dt)
; #pragma unroll
;                     for (int i = 0; i < 16; ++i) o[dt][i] *= alpha;
;             }
	v_pk_mul_f32 v[64:65], v[64:65], v[196:197] op_sel_hi:[1,0]
	v_pk_mul_f32 v[62:63], v[62:63], v[196:197] op_sel_hi:[1,0]
	v_pk_mul_f32 v[60:61], v[60:61], v[196:197] op_sel_hi:[1,0]
	v_pk_mul_f32 v[58:59], v[58:59], v[196:197] op_sel_hi:[1,0]
	v_pk_mul_f32 v[56:57], v[56:57], v[196:197] op_sel_hi:[1,0]
	v_pk_mul_f32 v[54:55], v[54:55], v[196:197] op_sel_hi:[1,0]
	v_pk_mul_f32 v[52:53], v[52:53], v[196:197] op_sel_hi:[1,0]
	v_pk_mul_f32 v[50:51], v[50:51], v[196:197] op_sel_hi:[1,0]
	v_pk_mul_f32 v[48:49], v[48:49], v[196:197] op_sel_hi:[1,0]
	v_pk_mul_f32 v[46:47], v[46:47], v[196:197] op_sel_hi:[1,0]
	v_pk_mul_f32 v[44:45], v[44:45], v[196:197] op_sel_hi:[1,0]
	v_pk_mul_f32 v[42:43], v[42:43], v[196:197] op_sel_hi:[1,0]
	v_pk_mul_f32 v[40:41], v[40:41], v[196:197] op_sel_hi:[1,0]
	v_pk_mul_f32 v[38:39], v[38:39], v[196:197] op_sel_hi:[1,0]
	v_pk_mul_f32 v[36:37], v[36:37], v[196:197] op_sel_hi:[1,0]
	v_pk_mul_f32 v[34:35], v[34:35], v[196:197] op_sel_hi:[1,0]
	v_pk_mul_f32 v[32:33], v[32:33], v[196:197] op_sel_hi:[1,0]
	v_pk_mul_f32 v[30:31], v[30:31], v[196:197] op_sel_hi:[1,0]
	v_pk_mul_f32 v[28:29], v[28:29], v[196:197] op_sel_hi:[1,0]
	v_pk_mul_f32 v[26:27], v[26:27], v[196:197] op_sel_hi:[1,0]
	v_pk_mul_f32 v[24:25], v[24:25], v[196:197] op_sel_hi:[1,0]
	v_pk_mul_f32 v[22:23], v[22:23], v[196:197] op_sel_hi:[1,0]
	v_pk_mul_f32 v[20:21], v[20:21], v[196:197] op_sel_hi:[1,0]
	v_pk_mul_f32 v[18:19], v[18:19], v[196:197] op_sel_hi:[1,0]
	v_pk_mul_f32 v[16:17], v[16:17], v[196:197] op_sel_hi:[1,0]
	v_pk_mul_f32 v[14:15], v[14:15], v[196:197] op_sel_hi:[1,0]
	v_pk_mul_f32 v[12:13], v[12:13], v[196:197] op_sel_hi:[1,0]
	v_pk_mul_f32 v[10:11], v[10:11], v[196:197] op_sel_hi:[1,0]
	v_pk_mul_f32 v[8:9], v[8:9], v[196:197] op_sel_hi:[1,0]
	v_pk_mul_f32 v[6:7], v[6:7], v[196:197] op_sel_hi:[1,0]
	v_pk_mul_f32 v[4:5], v[4:5], v[196:197] op_sel_hi:[1,0]
	v_pk_mul_f32 v[2:3], v[2:3], v[196:197] op_sel_hi:[1,0]

; #define LAS __attribute__((address_space(3)))
; DI float shfl_xor_l(float v, int lane, int m) { return __int_as_float(__builtin_amdgcn_ds_bpermute((lane ^ m) << 2, __float_as_int(v))); }
; #define VLD(dst, j, dt) do { LAS unsigned char* va_ = vb + (32 * (dt) + n) * VROW + (16 * (j) + 4 * g) * 2; const u32x2 lo_ = *(const LAS u32x2*)(va_), hi_ = *(const LAS u32x2*)(va_ + 16); dst = (u32x4){lo_.x, lo_.y, hi_.x, hi_.y}; } while (0)
; DI void attn_unit(LAS unsigned char* lds, int wid, int b, int h, int qb) {
;     ...
;         if (kt <= cq) {
;             LAS unsigned char* kb = lds + buf * ABUF; LAS unsigned char* vb = kb + KBYTES;
;             f32x16 s0, s1;
; #pragma unroll
;             for (int i = 0; i < 16; ++i) { s0[i] = 0.f; s1[i] = 0.f; }
;     ...
;             bf16x8 ka[3][2];
;             ka[0][0] = KLD(0, 0); ka[0][1] = KLD(0, 1); ka[1][0] = KLD(1, 0); ka[1][1] = KLD(1, 1);
; #pragma unroll
;             for (int ks = 0; ks < 12; ++ks) {
;                 if (ks + 2 < 12) { ka[(ks + 2) % 3][0] = KLD(ks + 2, 0); ka[(ks + 2) % 3][1] = KLD(ks + 2, 1); }
;                 s0 = __builtin_amdgcn_mfma_f32_32x32x16_bf16(ka[ks % 3][0], qf[ks], s0, 0, 0, 0); s1 = __builtin_amdgcn_mfma_f32_32x32x16_bf16(ka[ks % 3][1], qf[ks], s1, 0, 0, 0);
;                 __builtin_amdgcn_sched_barrier(0); }
;             u32x4 vf[2][4];
; #pragma unroll
;             for (int dt = 0; dt < 4; ++dt) VLD(vf[0][dt], 0, dt);
;             float mx = s0[0];
; #pragma unroll
;             for (int i = 1; i < 16; ++i) mx = fmaxf(mx, s0[i]);
; #pragma unroll
;             for (int i = 0; i < 16; ++i) mx = fmaxf(mx, s1[i]);
;             mx = fmaxf(mx, shfl_xor_l(mx, lane, 32));
;             const float mnew = fmaxf(mrow, mx), alpha = __builtin_amdgcn_exp2f(mrow - mnew); mrow = mnew;
;             float ls = 0.f;
; #pragma unroll
;             for (int i = 0; i < 16; ++i) { s0[i] = __builtin_amdgcn_exp2f(s0[i] - mnew); s1[i] = __builtin_amdgcn_exp2f(s1[i] - mnew); ls += s0[i] + s1[i]; }
;             lrow = lrow * alpha + ls;
;             if (__builtin_amdgcn_ballot_w64(alpha != 1.f) != 0ull) {
; #pragma unroll
;                 for (int dt = 0; dt < 4; ++dt)
; #pragma unroll
;                     for (int i = 0; i < 16; ++i) o[dt][i] *= alpha;
;             }
.LBB0_1086:
	s_or_b32 s61, s61, 2
	s_cmp_ge_u32 s61, s62
	s_cbranch_scc1 .LBB0_1090
	s_bitcmp1_b32 s63, 0
	s_cselect_b32 s61, 0xa800, 0
	s_add_i32 s61, s61, 0
	v_add3_u32 v162, s61, v199, v202
	ds_read_b128 v[66:69], v162
	ds_read_b128 v[146:149], v162 offset:32
	ds_read_b128 v[82:85], v162 offset:12800
	ds_read_b128 v[150:153], v162 offset:64
	ds_read_b128 v[154:157], v162 offset:12832
	ds_read_b128 v[158:161], v162 offset:12864
	s_waitcnt lgkmcnt(3)
	v_mfma_f32_32x32x16_bf16 v[82:97], v[82:85], v[142:145], 0
	v_mfma_f32_32x32x16_bf16 v[66:81], v[66:69], v[142:145], 0
	v_mfma_f32_32x32x16_bf16 v[66:81], v[146:149], v[138:141], v[66:81]
	ds_read_b128 v[142:145], v162 offset:96
	ds_read_b128 v[146:149], v162 offset:12896
	s_waitcnt lgkmcnt(3)
	v_mfma_f32_32x32x16_bf16 v[82:97], v[154:157], v[138:141], v[82:97]
	v_mfma_f32_32x32x16_bf16 v[66:81], v[150:153], v[134:137], v[66:81]
	ds_read_b128 v[138:141], v162 offset:128
	ds_read_b128 v[150:153], v162 offset:12928
	s_waitcnt lgkmcnt(4)
	v_mfma_f32_32x32x16_bf16 v[82:97], v[158:161], v[134:137], v[82:97]
	s_waitcnt lgkmcnt(3)
	v_mfma_f32_32x32x16_bf16 v[66:81], v[142:145], v[130:133], v[66:81]
	ds_read_b128 v[134:137], v162 offset:160
	ds_read_b128 v[142:145], v162 offset:12960
	s_waitcnt lgkmcnt(4)
	v_mfma_f32_32x32x16_bf16 v[82:97], v[146:149], v[130:133], v[82:97]
	s_waitcnt lgkmcnt(3)
	v_mfma_f32_32x32x16_bf16 v[66:81], v[138:141], v[126:129], v[66:81]
	ds_read_b128 v[130:133], v162 offset:192
	ds_read_b128 v[138:141], v162 offset:12992
	s_waitcnt lgkmcnt(4)
	v_mfma_f32_32x32x16_bf16 v[82:97], v[150:153], v[126:129], v[82:97]
	s_waitcnt lgkmcnt(3)
	v_mfma_f32_32x32x16_bf16 v[66:81], v[134:137], v[122:125], v[66:81]
	ds_read_b128 v[126:129], v162 offset:224
	ds_read_b128 v[134:137], v162 offset:13024
	s_waitcnt lgkmcnt(4)
	v_mfma_f32_32x32x16_bf16 v[82:97], v[142:145], v[122:125], v[82:97]
	s_waitcnt lgkmcnt(3)
	v_mfma_f32_32x32x16_bf16 v[66:81], v[130:133], v[118:121], v[66:81]
	ds_read_b128 v[122:125], v162 offset:256
	ds_read_b128 v[130:133], v162 offset:13056
	s_waitcnt lgkmcnt(4)
	v_mfma_f32_32x32x16_bf16 v[82:97], v[138:141], v[118:121], v[82:97]
	s_waitcnt lgkmcnt(3)
	v_mfma_f32_32x32x16_bf16 v[66:81], v[126:129], v[114:117], v[66:81]
	ds_read_b128 v[118:121], v162 offset:288
	ds_read_b128 v[126:129], v162 offset:13088
	s_waitcnt lgkmcnt(4)
	v_mfma_f32_32x32x16_bf16 v[82:97], v[134:137], v[114:117], v[82:97]
	s_waitcnt lgkmcnt(3)
	v_mfma_f32_32x32x16_bf16 v[66:81], v[122:125], v[110:113], v[66:81]
	ds_read_b128 v[114:117], v162 offset:320
	ds_read_b128 v[122:125], v162 offset:13120
	s_waitcnt lgkmcnt(4)
	v_mfma_f32_32x32x16_bf16 v[82:97], v[130:133], v[110:113], v[82:97]
	s_waitcnt lgkmcnt(3)
	v_mfma_f32_32x32x16_bf16 v[66:81], v[118:121], v[106:109], v[66:81]
	ds_read_b128 v[110:113], v162 offset:352
	ds_read_b128 v[118:121], v162 offset:13152
	s_waitcnt lgkmcnt(4)
	v_mfma_f32_32x32x16_bf16 v[82:97], v[126:129], v[106:109], v[82:97]
	s_waitcnt lgkmcnt(3)
	v_mfma_f32_32x32x16_bf16 v[66:81], v[114:117], v[102:105], v[66:81]
	s_waitcnt lgkmcnt(2)
	v_mfma_f32_32x32x16_bf16 v[82:97], v[122:125], v[102:105], v[82:97]
	s_waitcnt lgkmcnt(1)
	v_mfma_f32_32x32x16_bf16 v[66:81], v[110:113], v[98:101], v[66:81]
	v_add_u32_e32 v102, s61, v184
	v_add_u32_e32 v122, v102, v189
	v_add_u32_e32 v115, 0x6000, v122
	v_add_u32_e32 v116, 0x7000, v122
	v_add_u32_e32 v117, 0x8000, v122
	ds_read2_b64 v[102:105], v115 offset0:128 offset1:130
	ds_read2_b64 v[110:113], v116 offset0:160 offset1:162
	s_nop 4
	v_max_f32_e32 v106, v67, v67
	v_max_f32_e32 v107, v66, v66
	v_max_f32_e32 v106, v107, v106
	s_waitcnt lgkmcnt(2)
	v_mfma_f32_32x32x16_bf16 v[82:97], v[118:121], v[98:101], v[82:97]
	v_max3_f32 v106, v106, v68, v69
	v_max3_f32 v106, v106, v70, v71
	v_max3_f32 v106, v106, v72, v73
	v_max3_f32 v106, v106, v74, v75
	v_max3_f32 v106, v106, v76, v77
	v_max3_f32 v106, v106, v78, v79
	v_max3_f32 v106, v106, v80, v81
	s_nop 4
	v_max3_f32 v98, v106, v82, v83
	v_max3_f32 v98, v98, v84, v85
	v_max3_f32 v98, v98, v86, v87
	v_max3_f32 v98, v98, v88, v89
	v_max3_f32 v98, v98, v90, v91
	v_max3_f32 v98, v98, v92, v93
	v_max3_f32 v98, v98, v94, v95
	v_max3_f32 v98, v98, v96, v97
	ds_bpermute_b32 v99, v185, v98
	v_add_u32_e32 v118, 0x9000, v122
	ds_read2_b64 v[106:109], v117 offset0:192 offset1:194
	s_waitcnt lgkmcnt(1)
	v_max3_f32 v119, v203, v98, v99
	v_mov_b32_e32 v236, v203
	v_sub_f32_e32 v98, v203, v119
	v_cmp_gt_f32_e32 vcc, 0xc1000000, v98
	v_exp_f32_e32 v114, v98
	ds_read2_b64 v[98:101], v118 offset0:224 offset1:226
	s_cbranch_vccz .Lthr_1_keep
	v_pk_mul_f32 v[64:65], v[64:65], v[114:115] op_sel_hi:[1,0]
	v_pk_mul_f32 v[62:63], v[62:63], v[114:115] op_sel_hi:[1,0]
	v_pk_mul_f32 v[60:61], v[60:61], v[114:115] op_sel_hi:[1,0]
	v_pk_mul_f32 v[58:59], v[58:59], v[114:115] op_sel_hi:[1,0]
	v_pk_mul_f32 v[56:57], v[56:57], v[114:115] op_sel_hi:[1,0]
	v_pk_mul_f32 v[54:55], v[54:55], v[114:115] op_sel_hi:[1,0]
	v_pk_mul_f32 v[52:53], v[52:53], v[114:115] op_sel_hi:[1,0]
	v_pk_mul_f32 v[50:51], v[50:51], v[114:115] op_sel_hi:[1,0]
	v_pk_mul_f32 v[48:49], v[48:49], v[114:115] op_sel_hi:[1,0]
	v_pk_mul_f32 v[46:47], v[46:47], v[114:115] op_sel_hi:[1,0]
	v_pk_mul_f32 v[44:45], v[44:45], v[114:115] op_sel_hi:[1,0]
	v_pk_mul_f32 v[42:43], v[42:43], v[114:115] op_sel_hi:[1,0]
	v_pk_mul_f32 v[40:41], v[40:41], v[114:115] op_sel_hi:[1,0]
	v_pk_mul_f32 v[38:39], v[38:39], v[114:115] op_sel_hi:[1,0]
	v_pk_mul_f32 v[36:37], v[36:37], v[114:115] op_sel_hi:[1,0]
	v_pk_mul_f32 v[34:35], v[34:35], v[114:115] op_sel_hi:[1,0]
	v_pk_mul_f32 v[32:33], v[32:33], v[114:115] op_sel_hi:[1,0]
	v_pk_mul_f32 v[30:31], v[30:31], v[114:115] op_sel_hi:[1,0]
	v_pk_mul_f32 v[28:29], v[28:29], v[114:115] op_sel_hi:[1,0]
	v_pk_mul_f32 v[26:27], v[26:27], v[114:115] op_sel_hi:[1,0]
	v_pk_mul_f32 v[24:25], v[24:25], v[114:115] op_sel_hi:[1,0]
	v_pk_mul_f32 v[22:23], v[22:23], v[114:115] op_sel_hi:[1,0]
	v_pk_mul_f32 v[20:21], v[20:21], v[114:115] op_sel_hi:[1,0]
	v_pk_mul_f32 v[18:19], v[18:19], v[114:115] op_sel_hi:[1,0]
	v_pk_mul_f32 v[16:17], v[16:17], v[114:115] op_sel_hi:[1,0]
	v_pk_mul_f32 v[14:15], v[14:15], v[114:115] op_sel_hi:[1,0]
	v_pk_mul_f32 v[12:13], v[12:13], v[114:115] op_sel_hi:[1,0]
	v_pk_mul_f32 v[10:11], v[10:11], v[114:115] op_sel_hi:[1,0]
	v_pk_mul_f32 v[8:9], v[8:9], v[114:115] op_sel_hi:[1,0]
	v_pk_mul_f32 v[6:7], v[6:7], v[114:115] op_sel_hi:[1,0]
	v_pk_mul_f32 v[4:5], v[4:5], v[114:115] op_sel_hi:[1,0]
	v_pk_mul_f32 v[2:3], v[2:3], v[114:115] op_sel_hi:[1,0]

; #define LAS __attribute__((address_space(3)))
; DI float shfl_xor_l(float v, int lane, int m) { return __int_as_float(__builtin_amdgcn_ds_bpermute((lane ^ m) << 2, __float_as_int(v))); }
; DI void attn_unit(LAS unsigned char* lds, int wid, int b, int h, int qb) {
;     ...
;     A_LOAD(0); A_WRITE(0); __syncthreads();
;     for (int kt = 0; kt < nkt; ++kt) {
;         const int buf = kt & 1;
;         if (kt + 1 < nkt) A_LOAD(kt + 1);
;         if (kt <= cq) {
;             LAS unsigned char* kb = lds + buf * ABUF; LAS unsigned char* vb = kb + KBYTES;
;             f32x16 s0, s1;
; #pragma unroll
;             for (int i = 0; i < 16; ++i) { s0[i] = 0.f; s1[i] = 0.f; }
;     ...
;             bf16x8 ka[3][2];
;             ka[0][0] = KLD(0, 0); ka[0][1] = KLD(0, 1); ka[1][0] = KLD(1, 0); ka[1][1] = KLD(1, 1);
; #pragma unroll
;             for (int ks = 0; ks < 12; ++ks) {
;                 if (ks + 2 < 12) { ka[(ks + 2) % 3][0] = KLD(ks + 2, 0); ka[(ks + 2) % 3][1] = KLD(ks + 2, 1); }
;                 s0 = __builtin_amdgcn_mfma_f32_32x32x16_bf16(ka[ks % 3][0], qf[ks], s0, 0, 0, 0); s1 = __builtin_amdgcn_mfma_f32_32x32x16_bf16(ka[ks % 3][1], qf[ks], s1, 0, 0, 0);
;                 __builtin_amdgcn_sched_barrier(0); }
;             u32x4 vf[2][4];
; #pragma unroll
;             for (int dt = 0; dt < 4; ++dt) VLD(vf[0][dt], 0, dt);
;             float mx = s0[0];
; #pragma unroll
;             for (int i = 1; i < 16; ++i) mx = fmaxf(mx, s0[i]);
; #pragma unroll
;             for (int i = 0; i < 16; ++i) mx = fmaxf(mx, s1[i]);
;             mx = fmaxf(mx, shfl_xor_l(mx, lane, 32));
;             const float mnew = fmaxf(mrow, mx), alpha = __builtin_amdgcn_exp2f(mrow - mnew); mrow = mnew;
;             float ls = 0.f;
; #pragma unroll
;             for (int i = 0; i < 16; ++i) { s0[i] = __builtin_amdgcn_exp2f(s0[i] - mnew); s1[i] = __builtin_amdgcn_exp2f(s1[i] - mnew); ls += s0[i] + s1[i]; }
;             lrow = lrow * alpha + ls;
;             if (__builtin_amdgcn_ballot_w64(alpha != 1.f) != 0ull) {
; #pragma unroll
;                 for (int dt = 0; dt < 4; ++dt)
; #pragma unroll
;                     for (int i = 0; i < 16; ++i) o[dt][i] *= alpha;
;             }
.LBB0_1091:
	v_lshl_add_u64 v[2:3], s[26:27], 0, v[198:199]
	v_add_co_u32_e32 v4, vcc, 0x11140000, v2
	v_lshl_add_u64 v[14:15], s[26:27], 0, v[194:195]
	s_nop 0
	v_addc_co_u32_e32 v5, vcc, 0, v3, vcc
	v_add_co_u32_e32 v6, vcc, 0x11160000, v2
	v_lshl_add_u64 v[10:11], s[26:27], 0, v[196:197]
	s_nop 0
	v_addc_co_u32_e32 v7, vcc, 0, v3, vcc
	v_add_co_u32_e32 v80, vcc, 0x13100000, v14
	global_load_dwordx4 v[2:5], v[4:5], off
	s_nop 0
	global_load_dwordx4 v[6:9], v[6:7], off
	v_addc_co_u32_e32 v81, vcc, 0, v15, vcc
	v_add_co_u32_e32 v14, vcc, 0x13200000, v14
	global_load_dwordx4 v[10:13], v[10:11], off
	s_nop 0
	global_load_dwordx4 v[160:163], v[80:81], off offset:128
	v_addc_co_u32_e32 v15, vcc, 0, v15, vcc
	global_load_dwordx4 v[164:167], v[14:15], off offset:128
	s_and_b32 s18, s57, 1
	s_cmp_gt_u32 s57, s25
	s_cbranch_scc1 .LBB0_1095
	s_mul_i32 s19, s18, 0xa800
	s_add_i32 s19, s19, 0
	v_add3_u32 v0, s19, v193, v204
	ds_read_b128 v[80:83], v0
	ds_read_b128 v[168:171], v0 offset:32
	ds_read_b128 v[96:99], v0 offset:12800
	ds_read_b128 v[174:177], v0 offset:64
	ds_read_b128 v[178:181], v0 offset:12832
	ds_read_b128 v[206:209], v0 offset:12864
	s_waitcnt vmcnt(6) lgkmcnt(3)
	v_mfma_f32_32x32x16_bf16 v[96:111], v[96:99], v[156:159], 0
	v_mfma_f32_32x32x16_bf16 v[80:95], v[80:83], v[156:159], 0
	v_mfma_f32_32x32x16_bf16 v[80:95], v[168:171], v[152:155], v[80:95]
	ds_read_b128 v[168:171], v0 offset:96
	ds_read_b128 v[210:213], v0 offset:12896
	s_waitcnt lgkmcnt(3)
	v_mfma_f32_32x32x16_bf16 v[96:111], v[178:181], v[152:155], v[96:111]
	v_mfma_f32_32x32x16_bf16 v[80:95], v[174:177], v[148:151], v[80:95]
	ds_read_b128 v[174:177], v0 offset:128
	ds_read_b128 v[178:181], v0 offset:12928
	s_waitcnt lgkmcnt(4)
	v_mfma_f32_32x32x16_bf16 v[96:111], v[206:209], v[148:151], v[96:111]
	s_waitcnt lgkmcnt(3)
	v_mfma_f32_32x32x16_bf16 v[80:95], v[168:171], v[144:147], v[80:95]
	ds_read_b128 v[168:171], v0 offset:160
	ds_read_b128 v[206:209], v0 offset:12960
	s_waitcnt lgkmcnt(4)
	v_mfma_f32_32x32x16_bf16 v[96:111], v[210:213], v[144:147], v[96:111]
	s_waitcnt lgkmcnt(3)
	v_mfma_f32_32x32x16_bf16 v[80:95], v[174:177], v[140:143], v[80:95]
	ds_read_b128 v[174:177], v0 offset:192
	ds_read_b128 v[210:213], v0 offset:12992
	s_waitcnt lgkmcnt(4)
	v_mfma_f32_32x32x16_bf16 v[96:111], v[178:181], v[140:143], v[96:111]
	s_waitcnt lgkmcnt(3)
	v_mfma_f32_32x32x16_bf16 v[80:95], v[168:171], v[136:139], v[80:95]
	ds_read_b128 v[168:171], v0 offset:224
	ds_read_b128 v[178:181], v0 offset:13024
	s_waitcnt lgkmcnt(4)
	v_mfma_f32_32x32x16_bf16 v[96:111], v[206:209], v[136:139], v[96:111]
	s_waitcnt lgkmcnt(3)
	v_mfma_f32_32x32x16_bf16 v[80:95], v[174:177], v[132:135], v[80:95]
	ds_read_b128 v[174:177], v0 offset:256
	ds_read_b128 v[206:209], v0 offset:13056
	s_waitcnt lgkmcnt(4)
	v_mfma_f32_32x32x16_bf16 v[96:111], v[210:213], v[132:135], v[96:111]
	s_waitcnt lgkmcnt(3)
	v_mfma_f32_32x32x16_bf16 v[80:95], v[168:171], v[128:131], v[80:95]
	ds_read_b128 v[168:171], v0 offset:288
	ds_read_b128 v[210:213], v0 offset:13088
	s_waitcnt lgkmcnt(4)
	v_mfma_f32_32x32x16_bf16 v[96:111], v[178:181], v[128:131], v[96:111]
	s_waitcnt lgkmcnt(3)
	v_mfma_f32_32x32x16_bf16 v[80:95], v[174:177], v[124:127], v[80:95]
	ds_read_b128 v[174:177], v0 offset:320
	ds_read_b128 v[178:181], v0 offset:13120
	s_waitcnt lgkmcnt(4)
	v_mfma_f32_32x32x16_bf16 v[96:111], v[206:209], v[124:127], v[96:111]
	s_waitcnt lgkmcnt(3)
	v_mfma_f32_32x32x16_bf16 v[80:95], v[168:171], v[120:123], v[80:95]
	ds_read_b128 v[168:171], v0 offset:352
	ds_read_b128 v[206:209], v0 offset:13152
	s_waitcnt lgkmcnt(4)
	v_mfma_f32_32x32x16_bf16 v[96:111], v[210:213], v[120:123], v[96:111]
	s_waitcnt lgkmcnt(3)
	v_mfma_f32_32x32x16_bf16 v[80:95], v[174:177], v[116:119], v[80:95]
	s_waitcnt lgkmcnt(2)
	v_mfma_f32_32x32x16_bf16 v[96:111], v[178:181], v[116:119], v[96:111]
	s_waitcnt vmcnt(5) lgkmcnt(1)
	v_mfma_f32_32x32x16_bf16 v[80:95], v[168:171], v[112:115], v[80:95]
	v_add_u32_e32 v0, s19, v188
	v_add_u32_e32 v173, v0, v191
	v_add_u32_e32 v15, 0x6000, v173
	v_add_u32_e32 v205, 0x7000, v173
	ds_read2_b64 v[168:171], v15 offset0:128 offset1:130
	ds_read2_b64 v[180:183], v205 offset0:160 offset1:162
	s_nop 5
	v_max_f32_e32 v0, v81, v81
	v_max_f32_e32 v14, v80, v80
	v_max_f32_e32 v0, v14, v0
	s_waitcnt lgkmcnt(2)
	v_mfma_f32_32x32x16_bf16 v[96:111], v[206:209], v[112:115], v[96:111]
	v_max3_f32 v0, v0, v82, v83
	v_max3_f32 v0, v0, v84, v85
	v_max3_f32 v0, v0, v86, v87
	v_max3_f32 v0, v0, v88, v89
	v_max3_f32 v0, v0, v90, v91
	v_max3_f32 v0, v0, v92, v93
	v_max3_f32 v0, v0, v94, v95
	s_nop 4
	v_max3_f32 v0, v0, v96, v97
	v_max3_f32 v0, v0, v98, v99
	v_max3_f32 v0, v0, v100, v101
	v_max3_f32 v0, v0, v102, v103
	v_max3_f32 v0, v0, v104, v105
	v_max3_f32 v0, v0, v106, v107
	v_max3_f32 v0, v0, v108, v109
	v_max3_f32 v0, v0, v110, v111
	ds_bpermute_b32 v14, v189, v0
	v_add_u32_e32 v206, 0x8000, v173
	v_add_u32_e32 v207, 0x9000, v173
	ds_read2_b64 v[176:179], v206 offset0:192 offset1:194
	s_waitcnt lgkmcnt(1)
	v_max3_f32 v14, v172, v0, v14
	v_mov_b32_e32 v236, v172
	v_sub_f32_e32 v0, v172, v14
	v_cmp_gt_f32_e32 vcc, 0xc1000000, v0
	v_exp_f32_e32 v0, v0
	ds_read2_b64 v[172:175], v207 offset0:224 offset1:226
	s_cbranch_vccz .Lthr_2_keep
	v_pk_mul_f32 v[78:79], v[78:79], v[0:1] op_sel_hi:[1,0]
	v_pk_mul_f32 v[76:77], v[76:77], v[0:1] op_sel_hi:[1,0]
	v_pk_mul_f32 v[74:75], v[74:75], v[0:1] op_sel_hi:[1,0]
	v_pk_mul_f32 v[72:73], v[72:73], v[0:1] op_sel_hi:[1,0]
	v_pk_mul_f32 v[70:71], v[70:71], v[0:1] op_sel_hi:[1,0]
	v_pk_mul_f32 v[68:69], v[68:69], v[0:1] op_sel_hi:[1,0]
	v_pk_mul_f32 v[66:67], v[66:67], v[0:1] op_sel_hi:[1,0]
	v_pk_mul_f32 v[64:65], v[64:65], v[0:1] op_sel_hi:[1,0]
	v_pk_mul_f32 v[62:63], v[62:63], v[0:1] op_sel_hi:[1,0]
	v_pk_mul_f32 v[60:61], v[60:61], v[0:1] op_sel_hi:[1,0]
	v_pk_mul_f32 v[58:59], v[58:59], v[0:1] op_sel_hi:[1,0]
	v_pk_mul_f32 v[56:57], v[56:57], v[0:1] op_sel_hi:[1,0]
	v_pk_mul_f32 v[54:55], v[54:55], v[0:1] op_sel_hi:[1,0]
	v_pk_mul_f32 v[52:53], v[52:53], v[0:1] op_sel_hi:[1,0]
	v_pk_mul_f32 v[50:51], v[50:51], v[0:1] op_sel_hi:[1,0]
	v_pk_mul_f32 v[48:49], v[48:49], v[0:1] op_sel_hi:[1,0]
	v_pk_mul_f32 v[46:47], v[46:47], v[0:1] op_sel_hi:[1,0]
	v_pk_mul_f32 v[44:45], v[44:45], v[0:1] op_sel_hi:[1,0]
	v_pk_mul_f32 v[42:43], v[42:43], v[0:1] op_sel_hi:[1,0]
	v_pk_mul_f32 v[40:41], v[40:41], v[0:1] op_sel_hi:[1,0]
	v_pk_mul_f32 v[38:39], v[38:39], v[0:1] op_sel_hi:[1,0]
	v_pk_mul_f32 v[36:37], v[36:37], v[0:1] op_sel_hi:[1,0]
	v_pk_mul_f32 v[34:35], v[34:35], v[0:1] op_sel_hi:[1,0]
	v_pk_mul_f32 v[32:33], v[32:33], v[0:1] op_sel_hi:[1,0]
	v_pk_mul_f32 v[30:31], v[30:31], v[0:1] op_sel_hi:[1,0]
	v_pk_mul_f32 v[28:29], v[28:29], v[0:1] op_sel_hi:[1,0]
	v_pk_mul_f32 v[26:27], v[26:27], v[0:1] op_sel_hi:[1,0]
	v_pk_mul_f32 v[24:25], v[24:25], v[0:1] op_sel_hi:[1,0]
	v_pk_mul_f32 v[22:23], v[22:23], v[0:1] op_sel_hi:[1,0]
	v_pk_mul_f32 v[20:21], v[20:21], v[0:1] op_sel_hi:[1,0]
	v_pk_mul_f32 v[18:19], v[18:19], v[0:1] op_sel_hi:[1,0]
	v_pk_mul_f32 v[16:17], v[16:17], v[0:1] op_sel_hi:[1,0]

; #define LAS __attribute__((address_space(3)))
; DI float shfl_xor_l(float v, int lane, int m) { return __int_as_float(__builtin_amdgcn_ds_bpermute((lane ^ m) << 2, __float_as_int(v))); }
; #define VLD(dst, j, dt) do { LAS unsigned char* va_ = vb + (32 * (dt) + n) * VROW + (16 * (j) + 4 * g) * 2; const u32x2 lo_ = *(const LAS u32x2*)(va_), hi_ = *(const LAS u32x2*)(va_ + 16); dst = (u32x4){lo_.x, lo_.y, hi_.x, hi_.y}; } while (0)
; DI void attn_unit(LAS unsigned char* lds, int wid, int b, int h, int qb) {
;     ...
;         if (kt <= cq) {
;             LAS unsigned char* kb = lds + buf * ABUF; LAS unsigned char* vb = kb + KBYTES;
;             f32x16 s0, s1;
; #pragma unroll
;             for (int i = 0; i < 16; ++i) { s0[i] = 0.f; s1[i] = 0.f; }
;     ...
;             bf16x8 ka[3][2];
;             ka[0][0] = KLD(0, 0); ka[0][1] = KLD(0, 1); ka[1][0] = KLD(1, 0); ka[1][1] = KLD(1, 1);
; #pragma unroll
;             for (int ks = 0; ks < 12; ++ks) {
;                 if (ks + 2 < 12) { ka[(ks + 2) % 3][0] = KLD(ks + 2, 0); ka[(ks + 2) % 3][1] = KLD(ks + 2, 1); }
;                 s0 = __builtin_amdgcn_mfma_f32_32x32x16_bf16(ka[ks % 3][0], qf[ks], s0, 0, 0, 0); s1 = __builtin_amdgcn_mfma_f32_32x32x16_bf16(ka[ks % 3][1], qf[ks], s1, 0, 0, 0);
;                 __builtin_amdgcn_sched_barrier(0); }
;             u32x4 vf[2][4];
; #pragma unroll
;             for (int dt = 0; dt < 4; ++dt) VLD(vf[0][dt], 0, dt);
;             float mx = s0[0];
; #pragma unroll
;             for (int i = 1; i < 16; ++i) mx = fmaxf(mx, s0[i]);
; #pragma unroll
;             for (int i = 0; i < 16; ++i) mx = fmaxf(mx, s1[i]);
;             mx = fmaxf(mx, shfl_xor_l(mx, lane, 32));
;             const float mnew = fmaxf(mrow, mx), alpha = __builtin_amdgcn_exp2f(mrow - mnew); mrow = mnew;
;             float ls = 0.f;
; #pragma unroll
;             for (int i = 0; i < 16; ++i) { s0[i] = __builtin_amdgcn_exp2f(s0[i] - mnew); s1[i] = __builtin_amdgcn_exp2f(s1[i] - mnew); ls += s0[i] + s1[i]; }
;             lrow = lrow * alpha + ls;
;             if (__builtin_amdgcn_ballot_w64(alpha != 1.f) != 0ull) {
; #pragma unroll
;                 for (int dt = 0; dt < 4; ++dt)
; #pragma unroll
;                     for (int i = 0; i < 16; ++i) o[dt][i] *= alpha;
;             }
.LBB0_1098:
	s_lshl_b32 s18, s56, 2
	s_or_b32 s18, s18, 2
	s_cmp_ge_u32 s18, s25
	s_cbranch_scc1 .LBB0_1077
	s_bitcmp1_b32 s4, 0
	s_cselect_b32 s4, 0xa800, 0
	s_add_i32 s4, s4, 0
	v_add3_u32 v0, s4, v193, v204
	ds_read_b128 v[2:5], v0
	ds_read_b128 v[6:9], v0 offset:32
	s_waitcnt lgkmcnt(1)
	v_mfma_f32_32x32x16_bf16 v[80:95], v[2:5], v[156:159], 0
	ds_read_b128 v[2:5], v0 offset:12800
	ds_read_b128 v[10:13], v0 offset:64
	ds_read_b128 v[160:163], v0 offset:12832
	ds_read_b128 v[164:167], v0 offset:12864
	s_waitcnt lgkmcnt(3)
	v_mfma_f32_32x32x16_bf16 v[96:111], v[2:5], v[156:159], 0
	v_mfma_f32_32x32x16_bf16 v[80:95], v[6:9], v[152:155], v[80:95]
	ds_read_b128 v[2:5], v0 offset:96
	ds_read_b128 v[6:9], v0 offset:12896
	s_waitcnt lgkmcnt(3)
	v_mfma_f32_32x32x16_bf16 v[96:111], v[160:163], v[152:155], v[96:111]
	v_mfma_f32_32x32x16_bf16 v[80:95], v[10:13], v[148:151], v[80:95]
	ds_read_b128 v[10:13], v0 offset:128
	ds_read_b128 v[152:155], v0 offset:12928
	s_waitcnt lgkmcnt(4)
	v_mfma_f32_32x32x16_bf16 v[96:111], v[164:167], v[148:151], v[96:111]
	s_waitcnt lgkmcnt(3)
	v_mfma_f32_32x32x16_bf16 v[80:95], v[2:5], v[144:147], v[80:95]
	ds_read_b128 v[2:5], v0 offset:160
	ds_read_b128 v[148:151], v0 offset:12960
	s_waitcnt lgkmcnt(4)
	v_mfma_f32_32x32x16_bf16 v[96:111], v[6:9], v[144:147], v[96:111]
	s_waitcnt lgkmcnt(3)
	v_mfma_f32_32x32x16_bf16 v[80:95], v[10:13], v[140:143], v[80:95]
	ds_read_b128 v[6:9], v0 offset:192
	ds_read_b128 v[10:13], v0 offset:12992
	s_waitcnt lgkmcnt(4)
	v_mfma_f32_32x32x16_bf16 v[96:111], v[152:155], v[140:143], v[96:111]
	s_waitcnt lgkmcnt(3)
	v_mfma_f32_32x32x16_bf16 v[80:95], v[2:5], v[136:139], v[80:95]
	ds_read_b128 v[2:5], v0 offset:224
	ds_read_b128 v[140:143], v0 offset:13024
	s_waitcnt lgkmcnt(4)
	v_mfma_f32_32x32x16_bf16 v[96:111], v[148:151], v[136:139], v[96:111]
	s_waitcnt lgkmcnt(3)
	v_mfma_f32_32x32x16_bf16 v[80:95], v[6:9], v[132:135], v[80:95]
	ds_read_b128 v[6:9], v0 offset:256
	ds_read_b128 v[136:139], v0 offset:13056
	s_waitcnt lgkmcnt(4)
	v_mfma_f32_32x32x16_bf16 v[96:111], v[10:13], v[132:135], v[96:111]
	s_waitcnt lgkmcnt(3)
	v_mfma_f32_32x32x16_bf16 v[80:95], v[2:5], v[128:131], v[80:95]
	ds_read_b128 v[2:5], v0 offset:288
	ds_read_b128 v[10:13], v0 offset:13088
	s_waitcnt lgkmcnt(4)
	v_mfma_f32_32x32x16_bf16 v[96:111], v[140:143], v[128:131], v[96:111]
	s_waitcnt lgkmcnt(3)
	v_mfma_f32_32x32x16_bf16 v[80:95], v[6:9], v[124:127], v[80:95]
	ds_read_b128 v[6:9], v0 offset:320
	ds_read_b128 v[128:131], v0 offset:13120
	s_waitcnt lgkmcnt(4)
	v_mfma_f32_32x32x16_bf16 v[96:111], v[136:139], v[124:127], v[96:111]
	s_waitcnt lgkmcnt(3)
	v_mfma_f32_32x32x16_bf16 v[80:95], v[2:5], v[120:123], v[80:95]
	ds_read_b128 v[2:5], v0 offset:352
	ds_read_b128 v[124:127], v0 offset:13152
	s_waitcnt lgkmcnt(4)
	v_mfma_f32_32x32x16_bf16 v[96:111], v[10:13], v[120:123], v[96:111]
	s_waitcnt lgkmcnt(3)
	v_mfma_f32_32x32x16_bf16 v[80:95], v[6:9], v[116:119], v[80:95]
	s_waitcnt lgkmcnt(2)
	v_mfma_f32_32x32x16_bf16 v[96:111], v[128:131], v[116:119], v[96:111]
	s_waitcnt lgkmcnt(1)
	v_mfma_f32_32x32x16_bf16 v[80:95], v[2:5], v[112:115], v[80:95]
	v_add_u32_e32 v0, s4, v188
	v_add_u32_e32 v6, v0, v191
	v_add_u32_e32 v15, 0x6000, v6
	v_add_u32_e32 v116, 0x7000, v6
	v_add_u32_e32 v117, 0x8000, v6
	ds_read2_b64 v[2:5], v15 offset0:128 offset1:130
	ds_read2_b64 v[10:13], v117 offset0:192 offset1:194
	s_nop 4
	v_max_f32_e32 v0, v81, v81
	v_max_f32_e32 v7, v80, v80
	v_max_f32_e32 v0, v7, v0
	s_waitcnt lgkmcnt(2)
	v_mfma_f32_32x32x16_bf16 v[96:111], v[124:127], v[112:115], v[96:111]
	v_max3_f32 v0, v0, v82, v83
	v_max3_f32 v0, v0, v84, v85
	v_max3_f32 v0, v0, v86, v87
	v_max3_f32 v0, v0, v88, v89
	v_max3_f32 v0, v0, v90, v91
	v_max3_f32 v0, v0, v92, v93
	v_max3_f32 v0, v0, v94, v95
	s_nop 4
	v_max3_f32 v0, v0, v96, v97
	v_max3_f32 v0, v0, v98, v99
	v_max3_f32 v0, v0, v100, v101
	v_max3_f32 v0, v0, v102, v103
	v_max3_f32 v0, v0, v104, v105
	v_max3_f32 v0, v0, v106, v107
	v_max3_f32 v0, v0, v108, v109
	v_max3_f32 v0, v0, v110, v111
	ds_bpermute_b32 v7, v189, v0
	ds_read2_b64 v[112:115], v116 offset0:160 offset1:162
	s_waitcnt lgkmcnt(1)
	v_max3_f32 v118, v14, v0, v7
	v_mov_b32_e32 v236, v14
	v_sub_f32_e32 v0, v14, v118
	v_cmp_gt_f32_e32 vcc, 0xc1000000, v0
	v_add_u32_e32 v14, 0x9000, v6
	v_exp_f32_e32 v0, v0
	ds_read2_b64 v[6:9], v14 offset0:224 offset1:226
	s_cbranch_vccz .Lthr_3_keep
	v_pk_mul_f32 v[78:79], v[78:79], v[0:1] op_sel_hi:[1,0]
	v_pk_mul_f32 v[76:77], v[76:77], v[0:1] op_sel_hi:[1,0]
	v_pk_mul_f32 v[74:75], v[74:75], v[0:1] op_sel_hi:[1,0]
	v_pk_mul_f32 v[72:73], v[72:73], v[0:1] op_sel_hi:[1,0]
	v_pk_mul_f32 v[70:71], v[70:71], v[0:1] op_sel_hi:[1,0]
	v_pk_mul_f32 v[68:69], v[68:69], v[0:1] op_sel_hi:[1,0]
	v_pk_mul_f32 v[66:67], v[66:67], v[0:1] op_sel_hi:[1,0]
	v_pk_mul_f32 v[64:65], v[64:65], v[0:1] op_sel_hi:[1,0]
	v_pk_mul_f32 v[62:63], v[62:63], v[0:1] op_sel_hi:[1,0]
	v_pk_mul_f32 v[60:61], v[60:61], v[0:1] op_sel_hi:[1,0]
	v_pk_mul_f32 v[58:59], v[58:59], v[0:1] op_sel_hi:[1,0]
	v_pk_mul_f32 v[56:57], v[56:57], v[0:1] op_sel_hi:[1,0]
	v_pk_mul_f32 v[54:55], v[54:55], v[0:1] op_sel_hi:[1,0]
	v_pk_mul_f32 v[52:53], v[52:53], v[0:1] op_sel_hi:[1,0]
	v_pk_mul_f32 v[50:51], v[50:51], v[0:1] op_sel_hi:[1,0]
	v_pk_mul_f32 v[48:49], v[48:49], v[0:1] op_sel_hi:[1,0]
	v_pk_mul_f32 v[46:47], v[46:47], v[0:1] op_sel_hi:[1,0]
	v_pk_mul_f32 v[44:45], v[44:45], v[0:1] op_sel_hi:[1,0]
	v_pk_mul_f32 v[42:43], v[42:43], v[0:1] op_sel_hi:[1,0]
	v_pk_mul_f32 v[40:41], v[40:41], v[0:1] op_sel_hi:[1,0]
	v_pk_mul_f32 v[38:39], v[38:39], v[0:1] op_sel_hi:[1,0]
	v_pk_mul_f32 v[36:37], v[36:37], v[0:1] op_sel_hi:[1,0]
	v_pk_mul_f32 v[34:35], v[34:35], v[0:1] op_sel_hi:[1,0]
	v_pk_mul_f32 v[32:33], v[32:33], v[0:1] op_sel_hi:[1,0]
	v_pk_mul_f32 v[30:31], v[30:31], v[0:1] op_sel_hi:[1,0]
	v_pk_mul_f32 v[28:29], v[28:29], v[0:1] op_sel_hi:[1,0]
	v_pk_mul_f32 v[26:27], v[26:27], v[0:1] op_sel_hi:[1,0]
	v_pk_mul_f32 v[24:25], v[24:25], v[0:1] op_sel_hi:[1,0]
	v_pk_mul_f32 v[22:23], v[22:23], v[0:1] op_sel_hi:[1,0]
	v_pk_mul_f32 v[20:21], v[20:21], v[0:1] op_sel_hi:[1,0]
	v_pk_mul_f32 v[18:19], v[18:19], v[0:1] op_sel_hi:[1,0]
	v_pk_mul_f32 v[16:17], v[16:17], v[0:1] op_sel_hi:[1,0]
	s_branch .LBB0_1076
.Lthr_3_keep:
	v_mov_b32_e32 v118, v236
	v_mov_b32_e32 v0, 1.0
	s_branch .LBB0_1076
.Lthr_2_keep:
	v_mov_b32_e32 v14, v236
	v_mov_b32_e32 v0, 1.0
	s_branch .LBB0_1094
.Lthr_1_keep:
	v_mov_b32_e32 v119, v236
	v_mov_b32_e32 v114, 1.0
	s_branch .LBB0_1089
.Lthr_0_keep:
	v_mov_b32_e32 v203, v236
	v_mov_b32_e32 v196, 1.0
	s_branch .LBB0_1082
